# rwkv_prep second LoRA stage moved from scalar f32 FMA loops with broadcast LDS reads to v_mfma_f32_16x16x4_f32 (f32 operands, f32 accumulate) with LDS exchange
# speedup vs baseline: 1.1179x; 1.0323x over previous
.LBB0_365:
	s_or_b64 exec, exec, s[0:1]
	v_lshlrev_b32_e32 v9, 16, v9
	v_or_b32_e32 v110, 7, v10
	v_sub_f32_e32 v3, v3, v9
	v_lshlrev_b32_e32 v45, 10, v110
	s_movk_i32 s0, 0x400
	v_fmac_f32_e32 v9, v5, v3
	v_or_b32_e32 v3, v45, v4
	v_or_b32_sdwa v10, v2, s0 dst_sel:DWORD dst_unused:UNUSED_PAD src0_sel:BYTE_0 src1_sel:DWORD
	s_movk_i32 s0, 0x500
	ds_write2st64_b32 v3, v12, v9 offset1:64
	v_or_b32_sdwa v12, v2, s0 dst_sel:DWORD dst_unused:UNUSED_PAD src0_sel:BYTE_0 src1_sel:DWORD
	s_movk_i32 s0, 0x600
	v_or_b32_sdwa v14, v2, s0 dst_sel:DWORD dst_unused:UNUSED_PAD src0_sel:BYTE_0 src1_sel:DWORD
	s_movk_i32 s0, 0x700
	v_or_b32_sdwa v16, v2, s0 dst_sel:DWORD dst_unused:UNUSED_PAD src0_sel:BYTE_0 src1_sel:DWORD
	s_movk_i32 s0, 0x800
	v_or_b32_sdwa v18, v2, s0 dst_sel:DWORD dst_unused:UNUSED_PAD src0_sel:BYTE_0 src1_sel:DWORD
	s_movk_i32 s0, 0x900
	v_or_b32_sdwa v20, v2, s0 dst_sel:DWORD dst_unused:UNUSED_PAD src0_sel:BYTE_0 src1_sel:DWORD
	s_movk_i32 s0, 0xa00
	v_or_b32_sdwa v22, v2, s0 dst_sel:DWORD dst_unused:UNUSED_PAD src0_sel:BYTE_0 src1_sel:DWORD
	s_movk_i32 s0, 0xc00
	v_or_b32_sdwa v24, v2, s0 dst_sel:DWORD dst_unused:UNUSED_PAD src0_sel:BYTE_0 src1_sel:DWORD
	s_movk_i32 s0, 0xd00
	v_or_b32_sdwa v26, v2, s0 dst_sel:DWORD dst_unused:UNUSED_PAD src0_sel:BYTE_0 src1_sel:DWORD
	s_movk_i32 s0, 0xe00
	v_or_b32_sdwa v28, v2, s0 dst_sel:DWORD dst_unused:UNUSED_PAD src0_sel:BYTE_0 src1_sel:DWORD
	s_movk_i32 s0, 0xf00
	v_or_b32_sdwa v30, v2, s0 dst_sel:DWORD dst_unused:UNUSED_PAD src0_sel:BYTE_0 src1_sel:DWORD
	v_lshlrev_b32_e32 v5, 2, v24
	v_lshlrev_b32_e32 v13, 2, v26
	v_lshlrev_b32_e32 v15, 2, v28
	v_lshlrev_b32_e32 v32, 2, v30
	s_movk_i32 s0, 0xb00
	s_waitcnt lgkmcnt(0)
	s_barrier
	v_or_b32_sdwa v32, v2, s0 dst_sel:DWORD dst_unused:UNUSED_PAD src0_sel:BYTE_0 src1_sel:DWORD
	v_lshlrev_b32_e32 v108, 10, v8
	v_readfirstlane_b32 s28, v166
	v_and_b32_e32 v254, 15, v166
	v_bfe_u32 v255, v166, 4, 2
	s_nop 1
	s_lshr_b32 s28, s28, 6
	s_lshl_b32 s29, s28, 7
	v_lshlrev_b32_e32 v250, 10, v254
	v_lshl_add_u32 v250, v255, 4, v250
	v_lshlrev_b32_e32 v251, 12, v255
	v_lshl_add_u32 v251, v254, 2, v251
	v_add_u32_e32 v251, s29, v251
	v_add_u32_e32 v252, 0x12000, v251
	v_and_b32_e32 v253, 0xff, v166
	v_lshrrev_b32_e32 v254, 8, v166
	v_lshlrev_b32_e32 v253, 2, v253
	v_lshl_add_u32 v253, v254, 13, v253
	v_add_u32_e32 v253, 0x12000, v253
	s_add_u32 s30, s78, 0xc000
	s_addc_u32 s31, s79, 0
	v_mov_b32_e32 v196, 0
	v_mov_b32_e32 v197, 0
	v_mov_b32_e32 v198, 0
	v_mov_b32_e32 v199, 0
	v_mov_b32_e32 v200, 0
	v_mov_b32_e32 v201, 0
	v_mov_b32_e32 v202, 0
	v_mov_b32_e32 v203, 0
	v_mov_b32_e32 v204, 0
	v_mov_b32_e32 v205, 0
	v_mov_b32_e32 v206, 0
	v_mov_b32_e32 v207, 0
	v_mov_b32_e32 v208, 0
	v_mov_b32_e32 v209, 0
	v_mov_b32_e32 v210, 0
	v_mov_b32_e32 v211, 0
	v_mov_b32_e32 v212, 0
	v_mov_b32_e32 v213, 0
	v_mov_b32_e32 v214, 0
	v_mov_b32_e32 v215, 0
	v_mov_b32_e32 v216, 0
	v_mov_b32_e32 v217, 0
	v_mov_b32_e32 v218, 0
	v_mov_b32_e32 v219, 0
	s_add_u32 s26, s24, 0x0
	s_addc_u32 s27, s25, 0
	ds_read_b128 v[220:223], v250 offset:0
	global_load_dword v228, v251, s[26:27]
	global_load_dword v229, v251, s[26:27] offset:64
	global_load_dword v230, v251, s[26:27] offset:1024
	global_load_dword v231, v251, s[26:27] offset:1088
	global_load_dword v232, v251, s[26:27] offset:2048
	global_load_dword v233, v251, s[26:27] offset:2112
	global_load_dword v234, v251, s[26:27] offset:3072
	global_load_dword v235, v251, s[26:27] offset:3136
	s_add_u32 s26, s24, 0x4000
	s_addc_u32 s27, s25, 0
	ds_read_b128 v[224:227], v250 offset:64
	global_load_dword v236, v251, s[26:27]
	global_load_dword v237, v251, s[26:27] offset:64
	global_load_dword v238, v251, s[26:27] offset:1024
	global_load_dword v239, v251, s[26:27] offset:1088
	global_load_dword v246, v251, s[26:27] offset:2048
	global_load_dword v247, v251, s[26:27] offset:2112
	global_load_dword v248, v251, s[26:27] offset:3072
	global_load_dword v249, v251, s[26:27] offset:3136
	s_waitcnt vmcnt(8) lgkmcnt(1)
	v_mfma_f32_16x16x4_f32 v[196:199], v220, v228, v[196:199]
	v_mfma_f32_16x16x4_f32 v[200:203], v220, v229, v[200:203]
	v_mfma_f32_16x16x4_f32 v[196:199], v221, v230, v[196:199]
	v_mfma_f32_16x16x4_f32 v[200:203], v221, v231, v[200:203]
	v_mfma_f32_16x16x4_f32 v[196:199], v222, v232, v[196:199]
	v_mfma_f32_16x16x4_f32 v[200:203], v222, v233, v[200:203]
	v_mfma_f32_16x16x4_f32 v[196:199], v223, v234, v[196:199]
	v_mfma_f32_16x16x4_f32 v[200:203], v223, v235, v[200:203]
	s_add_u32 s26, s24, 0x8000
	s_addc_u32 s27, s25, 0
	ds_read_b128 v[220:223], v250 offset:128
	global_load_dword v228, v251, s[26:27]
	global_load_dword v229, v251, s[26:27] offset:64
	global_load_dword v230, v251, s[26:27] offset:1024
	global_load_dword v231, v251, s[26:27] offset:1088
	global_load_dword v232, v251, s[26:27] offset:2048
	global_load_dword v233, v251, s[26:27] offset:2112
	global_load_dword v234, v251, s[26:27] offset:3072
	global_load_dword v235, v251, s[26:27] offset:3136
	s_waitcnt vmcnt(8) lgkmcnt(1)
	v_mfma_f32_16x16x4_f32 v[196:199], v224, v236, v[196:199]
	v_mfma_f32_16x16x4_f32 v[200:203], v224, v237, v[200:203]
	v_mfma_f32_16x16x4_f32 v[196:199], v225, v238, v[196:199]
	v_mfma_f32_16x16x4_f32 v[200:203], v225, v239, v[200:203]
	v_mfma_f32_16x16x4_f32 v[196:199], v226, v246, v[196:199]
	v_mfma_f32_16x16x4_f32 v[200:203], v226, v247, v[200:203]
	v_mfma_f32_16x16x4_f32 v[196:199], v227, v248, v[196:199]
	v_mfma_f32_16x16x4_f32 v[200:203], v227, v249, v[200:203]
	s_add_u32 s26, s24, 0xc000
	s_addc_u32 s27, s25, 0
	ds_read_b128 v[224:227], v250 offset:192
	global_load_dword v236, v251, s[26:27]
	global_load_dword v237, v251, s[26:27] offset:64
	global_load_dword v238, v251, s[26:27] offset:1024
	global_load_dword v239, v251, s[26:27] offset:1088
	global_load_dword v246, v251, s[26:27] offset:2048
	global_load_dword v247, v251, s[26:27] offset:2112
	global_load_dword v248, v251, s[26:27] offset:3072
	global_load_dword v249, v251, s[26:27] offset:3136
	s_waitcnt vmcnt(8) lgkmcnt(1)
	v_mfma_f32_16x16x4_f32 v[196:199], v220, v228, v[196:199]
	v_mfma_f32_16x16x4_f32 v[200:203], v220, v229, v[200:203]
	v_mfma_f32_16x16x4_f32 v[196:199], v221, v230, v[196:199]
	v_mfma_f32_16x16x4_f32 v[200:203], v221, v231, v[200:203]
	v_mfma_f32_16x16x4_f32 v[196:199], v222, v232, v[196:199]
	v_mfma_f32_16x16x4_f32 v[200:203], v222, v233, v[200:203]
	v_mfma_f32_16x16x4_f32 v[196:199], v223, v234, v[196:199]
	v_mfma_f32_16x16x4_f32 v[200:203], v223, v235, v[200:203]
	s_add_u32 s26, s30, 0x0
	s_addc_u32 s27, s31, 0
	ds_read_b128 v[220:223], v250 offset:256
	global_load_dword v228, v251, s[26:27]
	global_load_dword v229, v251, s[26:27] offset:64
	global_load_dword v230, v251, s[26:27] offset:1024
	global_load_dword v231, v251, s[26:27] offset:1088
	global_load_dword v232, v251, s[26:27] offset:2048
	global_load_dword v233, v251, s[26:27] offset:2112
	global_load_dword v234, v251, s[26:27] offset:3072
	global_load_dword v235, v251, s[26:27] offset:3136
	s_waitcnt vmcnt(8) lgkmcnt(1)
	v_mfma_f32_16x16x4_f32 v[196:199], v224, v236, v[196:199]
	v_mfma_f32_16x16x4_f32 v[200:203], v224, v237, v[200:203]
	v_mfma_f32_16x16x4_f32 v[196:199], v225, v238, v[196:199]
	v_mfma_f32_16x16x4_f32 v[200:203], v225, v239, v[200:203]
	v_mfma_f32_16x16x4_f32 v[196:199], v226, v246, v[196:199]
	v_mfma_f32_16x16x4_f32 v[200:203], v226, v247, v[200:203]
	v_mfma_f32_16x16x4_f32 v[196:199], v227, v248, v[196:199]
	v_mfma_f32_16x16x4_f32 v[200:203], v227, v249, v[200:203]
	s_add_u32 s26, s30, 0x4000
	s_addc_u32 s27, s31, 0
	ds_read_b128 v[224:227], v250 offset:320
	global_load_dword v236, v251, s[26:27]
	global_load_dword v237, v251, s[26:27] offset:64
	global_load_dword v238, v251, s[26:27] offset:1024
	global_load_dword v239, v251, s[26:27] offset:1088
	global_load_dword v246, v251, s[26:27] offset:2048
	global_load_dword v247, v251, s[26:27] offset:2112
	global_load_dword v248, v251, s[26:27] offset:3072
	global_load_dword v249, v251, s[26:27] offset:3136
	s_waitcnt vmcnt(8) lgkmcnt(1)
	v_mfma_f32_16x16x4_f32 v[204:207], v220, v228, v[204:207]
	v_mfma_f32_16x16x4_f32 v[208:211], v220, v229, v[208:211]
	v_mfma_f32_16x16x4_f32 v[204:207], v221, v230, v[204:207]
	v_mfma_f32_16x16x4_f32 v[208:211], v221, v231, v[208:211]
	v_mfma_f32_16x16x4_f32 v[204:207], v222, v232, v[204:207]
	v_mfma_f32_16x16x4_f32 v[208:211], v222, v233, v[208:211]
	v_mfma_f32_16x16x4_f32 v[204:207], v223, v234, v[204:207]
	v_mfma_f32_16x16x4_f32 v[208:211], v223, v235, v[208:211]
	s_add_u32 s26, s30, 0x8000
	s_addc_u32 s27, s31, 0
	ds_read_b128 v[220:223], v250 offset:384
	global_load_dword v228, v251, s[26:27]
	global_load_dword v229, v251, s[26:27] offset:64
	global_load_dword v230, v251, s[26:27] offset:1024
	global_load_dword v231, v251, s[26:27] offset:1088
	global_load_dword v232, v251, s[26:27] offset:2048
	global_load_dword v233, v251, s[26:27] offset:2112
	global_load_dword v234, v251, s[26:27] offset:3072
	global_load_dword v235, v251, s[26:27] offset:3136
	s_waitcnt vmcnt(8) lgkmcnt(1)
	v_mfma_f32_16x16x4_f32 v[204:207], v224, v236, v[204:207]
	v_mfma_f32_16x16x4_f32 v[208:211], v224, v237, v[208:211]
	v_mfma_f32_16x16x4_f32 v[204:207], v225, v238, v[204:207]
	v_mfma_f32_16x16x4_f32 v[208:211], v225, v239, v[208:211]
	v_mfma_f32_16x16x4_f32 v[204:207], v226, v246, v[204:207]
	v_mfma_f32_16x16x4_f32 v[208:211], v226, v247, v[208:211]
	v_mfma_f32_16x16x4_f32 v[204:207], v227, v248, v[204:207]
	v_mfma_f32_16x16x4_f32 v[208:211], v227, v249, v[208:211]
	s_add_u32 s26, s30, 0xc000
	s_addc_u32 s27, s31, 0
	ds_read_b128 v[224:227], v250 offset:448
	global_load_dword v236, v251, s[26:27]
	global_load_dword v237, v251, s[26:27] offset:64
	global_load_dword v238, v251, s[26:27] offset:1024
	global_load_dword v239, v251, s[26:27] offset:1088
	global_load_dword v246, v251, s[26:27] offset:2048
	global_load_dword v247, v251, s[26:27] offset:2112
	global_load_dword v248, v251, s[26:27] offset:3072
	global_load_dword v249, v251, s[26:27] offset:3136
	s_waitcnt vmcnt(8) lgkmcnt(1)
	v_mfma_f32_16x16x4_f32 v[204:207], v220, v228, v[204:207]
	v_mfma_f32_16x16x4_f32 v[208:211], v220, v229, v[208:211]
	v_mfma_f32_16x16x4_f32 v[204:207], v221, v230, v[204:207]
	v_mfma_f32_16x16x4_f32 v[208:211], v221, v231, v[208:211]
	v_mfma_f32_16x16x4_f32 v[204:207], v222, v232, v[204:207]
	v_mfma_f32_16x16x4_f32 v[208:211], v222, v233, v[208:211]
	v_mfma_f32_16x16x4_f32 v[204:207], v223, v234, v[204:207]
	v_mfma_f32_16x16x4_f32 v[208:211], v223, v235, v[208:211]
	s_add_u32 s26, s21, 0x0
	s_addc_u32 s27, s60, 0
	ds_read_b128 v[220:223], v250 offset:512
	global_load_dword v228, v251, s[26:27]
	global_load_dword v229, v251, s[26:27] offset:64
	global_load_dword v230, v251, s[26:27] offset:1024
	global_load_dword v231, v251, s[26:27] offset:1088
	global_load_dword v232, v251, s[26:27] offset:2048
	global_load_dword v233, v251, s[26:27] offset:2112
	global_load_dword v234, v251, s[26:27] offset:3072
	global_load_dword v235, v251, s[26:27] offset:3136
	s_waitcnt vmcnt(8) lgkmcnt(1)
	v_mfma_f32_16x16x4_f32 v[204:207], v224, v236, v[204:207]
	v_mfma_f32_16x16x4_f32 v[208:211], v224, v237, v[208:211]
	v_mfma_f32_16x16x4_f32 v[204:207], v225, v238, v[204:207]
	v_mfma_f32_16x16x4_f32 v[208:211], v225, v239, v[208:211]
	v_mfma_f32_16x16x4_f32 v[204:207], v226, v246, v[204:207]
	v_mfma_f32_16x16x4_f32 v[208:211], v226, v247, v[208:211]
	v_mfma_f32_16x16x4_f32 v[204:207], v227, v248, v[204:207]
	v_mfma_f32_16x16x4_f32 v[208:211], v227, v249, v[208:211]
	s_add_u32 s26, s21, 0x4000
	s_addc_u32 s27, s60, 0
	ds_read_b128 v[224:227], v250 offset:576
	global_load_dword v236, v251, s[26:27]
	global_load_dword v237, v251, s[26:27] offset:64
	global_load_dword v238, v251, s[26:27] offset:1024
	global_load_dword v239, v251, s[26:27] offset:1088
	global_load_dword v246, v251, s[26:27] offset:2048
	global_load_dword v247, v251, s[26:27] offset:2112
	global_load_dword v248, v251, s[26:27] offset:3072
	global_load_dword v249, v251, s[26:27] offset:3136
	s_waitcnt vmcnt(8) lgkmcnt(1)
	v_mfma_f32_16x16x4_f32 v[212:215], v220, v228, v[212:215]
	v_mfma_f32_16x16x4_f32 v[216:219], v220, v229, v[216:219]
	v_mfma_f32_16x16x4_f32 v[212:215], v221, v230, v[212:215]
	v_mfma_f32_16x16x4_f32 v[216:219], v221, v231, v[216:219]
	v_mfma_f32_16x16x4_f32 v[212:215], v222, v232, v[212:215]
	v_mfma_f32_16x16x4_f32 v[216:219], v222, v233, v[216:219]
	v_mfma_f32_16x16x4_f32 v[212:215], v223, v234, v[212:215]
	v_mfma_f32_16x16x4_f32 v[216:219], v223, v235, v[216:219]
	s_add_u32 s26, s21, 0x8000
	s_addc_u32 s27, s60, 0
	ds_read_b128 v[220:223], v250 offset:640
	global_load_dword v228, v251, s[26:27]
	global_load_dword v229, v251, s[26:27] offset:64
	global_load_dword v230, v251, s[26:27] offset:1024
	global_load_dword v231, v251, s[26:27] offset:1088
	global_load_dword v232, v251, s[26:27] offset:2048
	global_load_dword v233, v251, s[26:27] offset:2112
	global_load_dword v234, v251, s[26:27] offset:3072
	global_load_dword v235, v251, s[26:27] offset:3136
	s_waitcnt vmcnt(8) lgkmcnt(1)
	v_mfma_f32_16x16x4_f32 v[212:215], v224, v236, v[212:215]
	v_mfma_f32_16x16x4_f32 v[216:219], v224, v237, v[216:219]
	v_mfma_f32_16x16x4_f32 v[212:215], v225, v238, v[212:215]
	v_mfma_f32_16x16x4_f32 v[216:219], v225, v239, v[216:219]
	v_mfma_f32_16x16x4_f32 v[212:215], v226, v246, v[212:215]
	v_mfma_f32_16x16x4_f32 v[216:219], v226, v247, v[216:219]
	v_mfma_f32_16x16x4_f32 v[212:215], v227, v248, v[212:215]
	v_mfma_f32_16x16x4_f32 v[216:219], v227, v249, v[216:219]
	s_add_u32 s26, s21, 0xc000
	s_addc_u32 s27, s60, 0
	ds_read_b128 v[224:227], v250 offset:704
	global_load_dword v236, v251, s[26:27]
	global_load_dword v237, v251, s[26:27] offset:64
	global_load_dword v238, v251, s[26:27] offset:1024
	global_load_dword v239, v251, s[26:27] offset:1088
	global_load_dword v246, v251, s[26:27] offset:2048
	global_load_dword v247, v251, s[26:27] offset:2112
	global_load_dword v248, v251, s[26:27] offset:3072
	global_load_dword v249, v251, s[26:27] offset:3136
	s_waitcnt vmcnt(8) lgkmcnt(1)
	v_mfma_f32_16x16x4_f32 v[212:215], v220, v228, v[212:215]
	v_mfma_f32_16x16x4_f32 v[216:219], v220, v229, v[216:219]
	v_mfma_f32_16x16x4_f32 v[212:215], v221, v230, v[212:215]
	v_mfma_f32_16x16x4_f32 v[216:219], v221, v231, v[216:219]
	v_mfma_f32_16x16x4_f32 v[212:215], v222, v232, v[212:215]
	v_mfma_f32_16x16x4_f32 v[216:219], v222, v233, v[216:219]
	v_mfma_f32_16x16x4_f32 v[212:215], v223, v234, v[212:215]
	v_mfma_f32_16x16x4_f32 v[216:219], v223, v235, v[216:219]
	s_add_u32 s26, s21, 0x10000
	s_addc_u32 s27, s60, 0
	ds_read_b128 v[220:223], v250 offset:768
	global_load_dword v228, v251, s[26:27]
	global_load_dword v229, v251, s[26:27] offset:64
	global_load_dword v230, v251, s[26:27] offset:1024
	global_load_dword v231, v251, s[26:27] offset:1088
	global_load_dword v232, v251, s[26:27] offset:2048
	global_load_dword v233, v251, s[26:27] offset:2112
	global_load_dword v234, v251, s[26:27] offset:3072
	global_load_dword v235, v251, s[26:27] offset:3136
	s_waitcnt vmcnt(8) lgkmcnt(1)
	v_mfma_f32_16x16x4_f32 v[212:215], v224, v236, v[212:215]
	v_mfma_f32_16x16x4_f32 v[216:219], v224, v237, v[216:219]
	v_mfma_f32_16x16x4_f32 v[212:215], v225, v238, v[212:215]
	v_mfma_f32_16x16x4_f32 v[216:219], v225, v239, v[216:219]
	v_mfma_f32_16x16x4_f32 v[212:215], v226, v246, v[212:215]
	v_mfma_f32_16x16x4_f32 v[216:219], v226, v247, v[216:219]
	v_mfma_f32_16x16x4_f32 v[212:215], v227, v248, v[212:215]
	v_mfma_f32_16x16x4_f32 v[216:219], v227, v249, v[216:219]
	s_add_u32 s26, s21, 0x14000
	s_addc_u32 s27, s60, 0
	ds_read_b128 v[224:227], v250 offset:832
	global_load_dword v236, v251, s[26:27]
	global_load_dword v237, v251, s[26:27] offset:64
	global_load_dword v238, v251, s[26:27] offset:1024
	global_load_dword v239, v251, s[26:27] offset:1088
	global_load_dword v246, v251, s[26:27] offset:2048
	global_load_dword v247, v251, s[26:27] offset:2112
	global_load_dword v248, v251, s[26:27] offset:3072
	global_load_dword v249, v251, s[26:27] offset:3136
	s_waitcnt vmcnt(8) lgkmcnt(1)
	v_mfma_f32_16x16x4_f32 v[212:215], v220, v228, v[212:215]
	v_mfma_f32_16x16x4_f32 v[216:219], v220, v229, v[216:219]
	v_mfma_f32_16x16x4_f32 v[212:215], v221, v230, v[212:215]
	v_mfma_f32_16x16x4_f32 v[216:219], v221, v231, v[216:219]
	v_mfma_f32_16x16x4_f32 v[212:215], v222, v232, v[212:215]
	v_mfma_f32_16x16x4_f32 v[216:219], v222, v233, v[216:219]
	v_mfma_f32_16x16x4_f32 v[212:215], v223, v234, v[212:215]
	v_mfma_f32_16x16x4_f32 v[216:219], v223, v235, v[216:219]
	s_add_u32 s26, s21, 0x18000
	s_addc_u32 s27, s60, 0
	ds_read_b128 v[220:223], v250 offset:896
	global_load_dword v228, v251, s[26:27]
	global_load_dword v229, v251, s[26:27] offset:64
	global_load_dword v230, v251, s[26:27] offset:1024
	global_load_dword v231, v251, s[26:27] offset:1088
	global_load_dword v232, v251, s[26:27] offset:2048
	global_load_dword v233, v251, s[26:27] offset:2112
	global_load_dword v234, v251, s[26:27] offset:3072
	global_load_dword v235, v251, s[26:27] offset:3136
	s_waitcnt vmcnt(8) lgkmcnt(1)
	v_mfma_f32_16x16x4_f32 v[212:215], v224, v236, v[212:215]
	v_mfma_f32_16x16x4_f32 v[216:219], v224, v237, v[216:219]
	v_mfma_f32_16x16x4_f32 v[212:215], v225, v238, v[212:215]
	v_mfma_f32_16x16x4_f32 v[216:219], v225, v239, v[216:219]
	v_mfma_f32_16x16x4_f32 v[212:215], v226, v246, v[212:215]
	v_mfma_f32_16x16x4_f32 v[216:219], v226, v247, v[216:219]
	v_mfma_f32_16x16x4_f32 v[212:215], v227, v248, v[212:215]
	v_mfma_f32_16x16x4_f32 v[216:219], v227, v249, v[216:219]
	s_add_u32 s26, s21, 0x1c000
	s_addc_u32 s27, s60, 0
	ds_read_b128 v[224:227], v250 offset:960
	global_load_dword v236, v251, s[26:27]
	global_load_dword v237, v251, s[26:27] offset:64
	global_load_dword v238, v251, s[26:27] offset:1024
	global_load_dword v239, v251, s[26:27] offset:1088
	global_load_dword v246, v251, s[26:27] offset:2048
	global_load_dword v247, v251, s[26:27] offset:2112
	global_load_dword v248, v251, s[26:27] offset:3072
	global_load_dword v249, v251, s[26:27] offset:3136
	s_waitcnt vmcnt(8) lgkmcnt(1)
	v_mfma_f32_16x16x4_f32 v[212:215], v220, v228, v[212:215]
	v_mfma_f32_16x16x4_f32 v[216:219], v220, v229, v[216:219]
	v_mfma_f32_16x16x4_f32 v[212:215], v221, v230, v[212:215]
	v_mfma_f32_16x16x4_f32 v[216:219], v221, v231, v[216:219]
	v_mfma_f32_16x16x4_f32 v[212:215], v222, v232, v[212:215]
	v_mfma_f32_16x16x4_f32 v[216:219], v222, v233, v[216:219]
	v_mfma_f32_16x16x4_f32 v[212:215], v223, v234, v[212:215]
	v_mfma_f32_16x16x4_f32 v[216:219], v223, v235, v[216:219]
	s_waitcnt vmcnt(0) lgkmcnt(0)
	v_mfma_f32_16x16x4_f32 v[212:215], v224, v236, v[212:215]
	v_mfma_f32_16x16x4_f32 v[216:219], v224, v237, v[216:219]
	v_mfma_f32_16x16x4_f32 v[212:215], v225, v238, v[212:215]
	v_mfma_f32_16x16x4_f32 v[216:219], v225, v239, v[216:219]
	v_mfma_f32_16x16x4_f32 v[212:215], v226, v246, v[212:215]
	v_mfma_f32_16x16x4_f32 v[216:219], v226, v247, v[216:219]
	v_mfma_f32_16x16x4_f32 v[212:215], v227, v248, v[212:215]
	v_mfma_f32_16x16x4_f32 v[216:219], v227, v249, v[216:219]
	s_nop 9
	s_nop 1
	ds_write_b32 v252, v196 offset:0
	ds_write_b32 v252, v197 offset:1024
	ds_write_b32 v252, v198 offset:2048
	ds_write_b32 v252, v199 offset:3072
	ds_write_b32 v252, v200 offset:64
	ds_write_b32 v252, v201 offset:1088
	ds_write_b32 v252, v202 offset:2112
	ds_write_b32 v252, v203 offset:3136
	ds_write_b32 v252, v204 offset:16384
	ds_write_b32 v252, v205 offset:17408
	ds_write_b32 v252, v206 offset:18432
	ds_write_b32 v252, v207 offset:19456
	ds_write_b32 v252, v208 offset:16448
	ds_write_b32 v252, v209 offset:17472
	ds_write_b32 v252, v210 offset:18496
	ds_write_b32 v252, v211 offset:19520
	ds_write_b32 v252, v212 offset:32768
	ds_write_b32 v252, v213 offset:33792
	ds_write_b32 v252, v214 offset:34816
	ds_write_b32 v252, v215 offset:35840
	ds_write_b32 v252, v216 offset:32832
	ds_write_b32 v252, v217 offset:33856
	ds_write_b32 v252, v218 offset:34880
	ds_write_b32 v252, v219 offset:35904
	s_waitcnt lgkmcnt(0)
	s_barrier
	ds_read_b32 v107, v253 offset:0
	ds_read_b32 v104, v253 offset:1024
	ds_read_b32 v101, v253 offset:2048
	ds_read_b32 v96, v253 offset:3072
	ds_read_b32 v91, v253 offset:4096
	ds_read_b32 v83, v253 offset:5120
	ds_read_b32 v69, v253 offset:6144
	ds_read_b32 v53, v253 offset:7168
	ds_read_b32 v106, v253 offset:16384
	ds_read_b32 v103, v253 offset:17408
	ds_read_b32 v100, v253 offset:18432
	ds_read_b32 v95, v253 offset:19456
	ds_read_b32 v89, v253 offset:20480
	ds_read_b32 v81, v253 offset:21504
	ds_read_b32 v63, v253 offset:22528
	ds_read_b32 v51, v253 offset:23552
	ds_read_b32 v105, v253 offset:32768
	ds_read_b32 v102, v253 offset:33792
	ds_read_b32 v99, v253 offset:34816
	ds_read_b32 v93, v253 offset:35840
	ds_read_b32 v85, v253 offset:36864
	ds_read_b32 v75, v253 offset:37888
	ds_read_b32 v57, v253 offset:38912
	ds_read_b32 v3, v253 offset:39936
	s_waitcnt lgkmcnt(0)
